# in-proj GEMM: next tile's first staging loads hoisted in front of the epilogue stores, first K-loop vmcnt wait relaxed to vmcnt(22)
# speedup vs baseline: 1.0046x; 1.0015x over previous
.LBB0_913:
	v_readlane_b32 s10, v254, 25
	v_readlane_b32 s11, v254, 26
	s_load_dwordx2 s[14:15], s[10:11], 0x118
	v_readlane_b32 s16, v254, 29
	v_readlane_b32 s17, v254, 30
	s_mov_b32 s20, s16
	v_lshl_add_u64 v[8:9], v[8:9], 0, s[92:93]
	s_waitcnt lgkmcnt(0)
	s_add_u32 s10, s14, 0xb134000
	s_addc_u32 s11, s15, 0
	s_add_u32 s12, s14, 0x8134000
	s_addc_u32 s13, s15, 0
	s_add_u32 s14, s14, 0xc934000
	s_addc_u32 s15, s15, 0
	s_ashr_i32 s21, s16, 31
	v_writelane_b32 v254, s16, 29
	s_waitcnt vmcnt(4)
	s_barrier
	v_lshl_add_u64 v[6:7], v[6:7], 0, s[92:93]
	v_writelane_b32 v254, s17, 30
	s_lshl_b64 s[16:17], s[20:21], 6
	s_add_u32 s16, s4, s16
	s_addc_u32 s17, s5, s17
	s_lshl_b32 s4, s19, 12
	s_add_i32 m0, s38, 0x18000
	s_lshl_b32 s7, s18, 13
	s_and_b32 s9, s4, 0x3000
	global_load_lds_dwordx4 v[8:9], off
	s_add_i32 m0, s38, 0x1a000
	s_add_i32 s42, s38, 0x8000
	s_add_i32 s43, s38, 0xa000
	global_load_lds_dwordx4 v[6:7], off
	v_lshl_add_u64 v[4:5], v[4:5], 0, s[92:93]
	s_mov_b32 m0, s42
	s_add_u32 s4, s26, 0x40080
	global_load_lds_dwordx4 v[4:5], off
	v_lshl_add_u64 v[2:3], v[2:3], 0, s[92:93]
	s_mov_b32 m0, s43
	s_addc_u32 s5, s27, 0
	global_load_lds_dwordx4 v[2:3], off
	s_add_i32 m0, s38, 0x1c000
	v_lshl_add_u64 v[2:3], s[4:5], 0, v[130:131]
	global_load_lds_dwordx4 v[2:3], off
	v_lshl_add_u64 v[2:3], s[4:5], 0, v[132:133]
	s_add_i32 m0, s38, 0x1e000
	s_ashr_i32 s44, s0, 31
	global_load_lds_dwordx4 v[2:3], off
	v_and_b32_e32 v2, 15, v0
	v_and_b32_e32 v3, 48, v0
	v_lshlrev_b32_e32 v0, 2, v0
	v_lshlrev_b32_e32 v2, 6, v2
	v_and_b32_e32 v0, 32, v0
	v_or_b32_e32 v4, v2, v3
	v_bitop3_b32 v2, v2, v0, v3 bitop3:0x36
	v_or_b32_e32 v150, s9, v2
	v_lshlrev_b32_e32 v2, 14, v13
	v_and_b32_e32 v2, 0xffff8000, v2
	v_lshl_add_u32 v2, v14, 11, v2
	v_and_b32_e32 v3, 1, v13
	v_lshl_or_b32 v2, v3, 6, v2
	v_lshl_add_u32 v134, v15, 1, v2
	v_lshlrev_b32_e32 v2, 14, v10
	v_and_b32_e32 v2, 0xffff8000, v2
	s_waitcnt vmcnt(6)
	v_lshl_add_u32 v2, v11, 11, v2
	v_and_b32_e32 v3, 1, v10
	v_bitop3_b32 v0, v4, s7, v0 bitop3:0xde
	v_lshl_or_b32 v2, v3, 6, v2
	s_ashr_i32 s45, s1, 31
	v_mov_b32_e32 v135, v1
	v_lshl_add_u32 v136, v12, 1, v2
	v_mov_b32_e32 v137, v1
	s_mov_b32 s46, 0
	v_add_u32_e32 v151, 0, v0
	s_barrier
	s_mov_b32 s98, 0
	s_branch .LBB0_915

.LBB0_918:
	s_add_u32 s28, s26, 0xfffc0080
	s_addc_u32 s29, s27, -1
	s_add_i32 s48, 0, 0x10000
	v_add_u32_e32 v0, s48, v150
	ds_read_b128 v[138:141], v0
	ds_read_b128 v[142:145], v0 offset:1024
	ds_read_b128 v[146:149], v0 offset:2048
	ds_read_b128 v[152:155], v0 offset:3072
	s_cmp_eq_u32 s47, 12
	s_cselect_b32 s31, s7, s29
	s_cselect_b32 s30, s9, s28
	s_cselect_b32 s29, s19, s35
	s_cselect_b32 s28, s21, s34
	v_lshl_add_u64 v[160:161], s[26:27], 0, v[136:137]
	s_add_i32 m0, s38, 0xc000
	ds_read_b128 v[156:159], v151
	ds_read_b128 v[176:179], v151 offset:1024
	ds_read_b128 v[180:183], v151 offset:2048
	ds_read_b128 v[184:187], v151 offset:3072
	ds_read_b128 v[188:191], v151 offset:4096
	ds_read_b128 v[192:195], v151 offset:5120
	ds_read_b128 v[196:199], v151 offset:6144
	ds_read_b128 v[230:233], v151 offset:7168
	s_cmp_lg_u32 s98, 0
	s_cbranch_scc1 .Lip_skip_p10
	global_load_lds_dwordx4 v[160:161], off
.Lip_skip_p10:
	v_lshl_add_u64 v[160:161], s[26:27], 0, v[134:135]
	s_add_i32 m0, s38, 0xe000
	s_nop 0
	s_cmp_lg_u32 s98, 0
	s_cbranch_scc1 .Lip_skip_p11
	global_load_lds_dwordx4 v[160:161], off
.Lip_skip_p11:
	s_waitcnt lgkmcnt(8)
	s_barrier
	s_waitcnt lgkmcnt(0)
	s_setprio 1
	s_waitcnt lgkmcnt(0)
	v_mfma_f32_16x16x32_bf16 v[126:129], v[138:141], v[156:159], v[126:129]
	v_mfma_f32_16x16x32_bf16 v[122:125], v[146:149], v[156:159], v[122:125]
	v_mfma_f32_16x16x32_bf16 v[110:113], v[138:141], v[180:183], v[110:113]
	v_mfma_f32_16x16x32_bf16 v[106:109], v[146:149], v[180:183], v[106:109]
	v_mfma_f32_16x16x32_bf16 v[94:97], v[138:141], v[188:191], v[94:97]
	v_mfma_f32_16x16x32_bf16 v[90:93], v[146:149], v[188:191], v[90:93]
	v_mfma_f32_16x16x32_bf16 v[78:81], v[138:141], v[196:199], v[78:81]
	v_mfma_f32_16x16x32_bf16 v[74:77], v[146:149], v[196:199], v[74:77]
	v_mfma_f32_16x16x32_bf16 v[126:129], v[142:145], v[176:179], v[126:129]
	v_mfma_f32_16x16x32_bf16 v[122:125], v[152:155], v[176:179], v[122:125]
	v_mfma_f32_16x16x32_bf16 v[110:113], v[142:145], v[184:187], v[110:113]
	v_mfma_f32_16x16x32_bf16 v[106:109], v[152:155], v[184:187], v[106:109]
	v_mfma_f32_16x16x32_bf16 v[94:97], v[142:145], v[192:195], v[94:97]
	v_mfma_f32_16x16x32_bf16 v[90:93], v[152:155], v[192:195], v[90:93]
	v_mfma_f32_16x16x32_bf16 v[78:81], v[142:145], v[230:233], v[78:81]
	v_mfma_f32_16x16x32_bf16 v[74:77], v[152:155], v[230:233], v[74:77]
	s_setprio 0
	s_barrier
	s_add_i32 s50, 0, 0x14000
	s_add_i32 s48, s48, s37
	v_add_u32_e32 v0, s50, v150
	v_lshl_add_u64 v[160:161], s[28:29], 0, v[130:131]
	s_mov_b32 m0, s48
	ds_read_b128 v[234:237], v0
	ds_read_b128 v[238:241], v0 offset:1024
	ds_read_b128 v[242:245], v0 offset:2048
	ds_read_b128 v[246:249], v0 offset:3072
	global_load_lds_dwordx4 v[160:161], off
	v_lshl_add_u64 v[200:201], s[28:29], 0, v[132:133]
	s_add_i32 m0, s48, 0x2000
	s_nop 0
	global_load_lds_dwordx4 v[200:201], off
	s_barrier
	s_waitcnt lgkmcnt(0)
	s_setprio 1
	s_waitcnt lgkmcnt(0)
	v_mfma_f32_16x16x32_bf16 v[118:121], v[234:237], v[156:159], v[118:121]
	v_mfma_f32_16x16x32_bf16 v[114:117], v[242:245], v[156:159], v[114:117]
	v_mfma_f32_16x16x32_bf16 v[102:105], v[234:237], v[180:183], v[102:105]
	v_mfma_f32_16x16x32_bf16 v[98:101], v[242:245], v[180:183], v[98:101]
	v_mfma_f32_16x16x32_bf16 v[86:89], v[234:237], v[188:191], v[86:89]
	v_mfma_f32_16x16x32_bf16 v[82:85], v[242:245], v[188:191], v[82:85]
	v_mfma_f32_16x16x32_bf16 v[70:73], v[234:237], v[196:199], v[70:73]
	v_mfma_f32_16x16x32_bf16 v[66:69], v[242:245], v[196:199], v[66:69]
	v_mfma_f32_16x16x32_bf16 v[118:121], v[238:241], v[176:179], v[118:121]
	v_mfma_f32_16x16x32_bf16 v[114:117], v[246:249], v[176:179], v[114:117]
	v_mfma_f32_16x16x32_bf16 v[102:105], v[238:241], v[184:187], v[102:105]
	v_mfma_f32_16x16x32_bf16 v[98:101], v[246:249], v[184:187], v[98:101]
	v_mfma_f32_16x16x32_bf16 v[86:89], v[238:241], v[192:195], v[86:89]
	v_mfma_f32_16x16x32_bf16 v[82:85], v[246:249], v[192:195], v[82:85]
	v_mfma_f32_16x16x32_bf16 v[70:73], v[238:241], v[230:233], v[70:73]
	v_mfma_f32_16x16x32_bf16 v[66:69], v[246:249], v[230:233], v[66:69]
	s_setprio 0
	s_mov_b32 m0, s38
	v_lshl_add_u64 v[250:251], s[30:31], 0, v[130:131]
	s_barrier
	ds_read_b128 v[156:159], v151 offset:16384
	ds_read_b128 v[176:179], v151 offset:17408
	ds_read_b128 v[180:183], v151 offset:18432
	ds_read_b128 v[184:187], v151 offset:19456
	ds_read_b128 v[188:191], v151 offset:20480
	ds_read_b128 v[192:195], v151 offset:21504
	ds_read_b128 v[196:199], v151 offset:22528
	ds_read_b128 v[230:233], v151 offset:23552
	global_load_lds_dwordx4 v[250:251], off
	v_lshl_add_u64 v[252:253], s[30:31], 0, v[132:133]
	s_mov_b32 m0, s39
	s_nop 0
	global_load_lds_dwordx4 v[252:253], off
	s_barrier
	s_waitcnt lgkmcnt(0)
	s_setprio 1
	s_waitcnt lgkmcnt(0)
	v_mfma_f32_16x16x32_bf16 v[62:65], v[138:141], v[156:159], v[62:65]
	v_mfma_f32_16x16x32_bf16 v[58:61], v[146:149], v[156:159], v[58:61]
	v_mfma_f32_16x16x32_bf16 v[46:49], v[138:141], v[180:183], v[46:49]
	v_mfma_f32_16x16x32_bf16 v[42:45], v[146:149], v[180:183], v[42:45]
	v_mfma_f32_16x16x32_bf16 v[30:33], v[138:141], v[188:191], v[30:33]
	v_mfma_f32_16x16x32_bf16 v[26:29], v[146:149], v[188:191], v[26:29]
	v_mfma_f32_16x16x32_bf16 v[14:17], v[138:141], v[196:199], v[14:17]
	v_mfma_f32_16x16x32_bf16 v[10:13], v[146:149], v[196:199], v[10:13]
	v_mfma_f32_16x16x32_bf16 v[62:65], v[142:145], v[176:179], v[62:65]
	v_mfma_f32_16x16x32_bf16 v[58:61], v[152:155], v[176:179], v[58:61]
	v_mfma_f32_16x16x32_bf16 v[46:49], v[142:145], v[184:187], v[46:49]
	v_mfma_f32_16x16x32_bf16 v[42:45], v[152:155], v[184:187], v[42:45]
	v_mfma_f32_16x16x32_bf16 v[30:33], v[142:145], v[192:195], v[30:33]
	v_mfma_f32_16x16x32_bf16 v[26:29], v[152:155], v[192:195], v[26:29]
	v_mfma_f32_16x16x32_bf16 v[14:17], v[142:145], v[230:233], v[14:17]
	v_mfma_f32_16x16x32_bf16 v[10:13], v[152:155], v[230:233], v[10:13]
	s_setprio 0
	s_barrier
	s_add_u32 s48, s28, 0x40000
	s_addc_u32 s49, s29, 0
	s_add_i32 s50, s50, s37
	v_lshl_add_u64 v[138:139], s[48:49], 0, v[130:131]
	s_mov_b32 m0, s50
	s_nop 0
	global_load_lds_dwordx4 v[138:139], off
	v_lshl_add_u64 v[138:139], s[48:49], 0, v[132:133]
	s_add_i32 m0, s50, 0x2000
	s_nop 0
	global_load_lds_dwordx4 v[138:139], off
	s_cmp_lg_u32 s98, 0
	s_cbranch_scc1 .Lip_relax
	s_waitcnt vmcnt(6)
	s_branch .Lip_w4
.Lip_relax:
	s_waitcnt vmcnt(22)
	s_mov_b32 s98, 0
.Lip_w4:
	s_barrier
	s_setprio 1
	v_mfma_f32_16x16x32_bf16 v[54:57], v[234:237], v[156:159], v[54:57]
	v_mfma_f32_16x16x32_bf16 v[50:53], v[242:245], v[156:159], v[50:53]
	v_mfma_f32_16x16x32_bf16 v[38:41], v[234:237], v[180:183], v[38:41]
	v_mfma_f32_16x16x32_bf16 v[34:37], v[242:245], v[180:183], v[34:37]
	v_mfma_f32_16x16x32_bf16 v[22:25], v[234:237], v[188:191], v[22:25]
	v_mfma_f32_16x16x32_bf16 v[18:21], v[242:245], v[188:191], v[18:21]
	v_mfma_f32_16x16x32_bf16 v[6:9], v[234:237], v[196:199], v[6:9]
	v_mfma_f32_16x16x32_bf16 v[2:5], v[242:245], v[196:199], v[2:5]
	v_mfma_f32_16x16x32_bf16 v[54:57], v[238:241], v[176:179], v[54:57]
	v_mfma_f32_16x16x32_bf16 v[50:53], v[246:249], v[176:179], v[50:53]
	v_mfma_f32_16x16x32_bf16 v[38:41], v[238:241], v[184:187], v[38:41]
	v_mfma_f32_16x16x32_bf16 v[34:37], v[246:249], v[184:187], v[34:37]
	v_mfma_f32_16x16x32_bf16 v[22:25], v[238:241], v[192:195], v[22:25]
	v_mfma_f32_16x16x32_bf16 v[18:21], v[246:249], v[192:195], v[18:21]
	v_mfma_f32_16x16x32_bf16 v[6:9], v[238:241], v[230:233], v[6:9]
	v_mfma_f32_16x16x32_bf16 v[2:5], v[246:249], v[230:233], v[2:5]
	s_setprio 0
	s_add_i32 s48, 0, 0x18000
	v_add_u32_e32 v0, s48, v150
	s_barrier
	ds_read_b128 v[138:141], v0
	ds_read_b128 v[142:145], v0 offset:1024
	ds_read_b128 v[146:149], v0 offset:2048
	ds_read_b128 v[152:155], v0 offset:3072
	s_add_u32 s30, s30, 0x40000
	s_addc_u32 s31, s31, 0
	s_mov_b32 m0, s40
	v_lshl_add_u64 v[234:235], s[30:31], 0, v[130:131]
	ds_read_b128 v[156:159], v151 offset:32768
	ds_read_b128 v[176:179], v151 offset:33792
	ds_read_b128 v[180:183], v151 offset:34816
	ds_read_b128 v[184:187], v151 offset:35840
	ds_read_b128 v[188:191], v151 offset:36864
	ds_read_b128 v[192:195], v151 offset:37888
	ds_read_b128 v[196:199], v151 offset:38912
	ds_read_b128 v[230:233], v151 offset:39936
	global_load_lds_dwordx4 v[234:235], off
	v_lshl_add_u64 v[234:235], s[30:31], 0, v[132:133]
	s_mov_b32 m0, s41
	s_nop 0
	global_load_lds_dwordx4 v[234:235], off
	s_waitcnt lgkmcnt(8)
	s_barrier
	s_waitcnt lgkmcnt(0)
	s_setprio 1
	s_waitcnt lgkmcnt(0)
	v_mfma_f32_16x16x32_bf16 v[126:129], v[138:141], v[156:159], v[126:129]
	v_mfma_f32_16x16x32_bf16 v[122:125], v[146:149], v[156:159], v[122:125]
	v_mfma_f32_16x16x32_bf16 v[110:113], v[138:141], v[180:183], v[110:113]
	v_mfma_f32_16x16x32_bf16 v[106:109], v[146:149], v[180:183], v[106:109]
	v_mfma_f32_16x16x32_bf16 v[94:97], v[138:141], v[188:191], v[94:97]
	v_mfma_f32_16x16x32_bf16 v[90:93], v[146:149], v[188:191], v[90:93]
	v_mfma_f32_16x16x32_bf16 v[78:81], v[138:141], v[196:199], v[78:81]
	v_mfma_f32_16x16x32_bf16 v[74:77], v[146:149], v[196:199], v[74:77]
	v_mfma_f32_16x16x32_bf16 v[126:129], v[142:145], v[176:179], v[126:129]
	v_mfma_f32_16x16x32_bf16 v[122:125], v[152:155], v[176:179], v[122:125]
	v_mfma_f32_16x16x32_bf16 v[110:113], v[142:145], v[184:187], v[110:113]
	v_mfma_f32_16x16x32_bf16 v[106:109], v[152:155], v[184:187], v[106:109]
	v_mfma_f32_16x16x32_bf16 v[94:97], v[142:145], v[192:195], v[94:97]
	v_mfma_f32_16x16x32_bf16 v[90:93], v[152:155], v[192:195], v[90:93]
	v_mfma_f32_16x16x32_bf16 v[78:81], v[142:145], v[230:233], v[78:81]
	v_mfma_f32_16x16x32_bf16 v[74:77], v[152:155], v[230:233], v[74:77]
	s_setprio 0
	s_barrier
	s_add_i32 s30, 0, 0x1c000
	s_add_i32 s31, s48, s37
	v_add_u32_e32 v0, s30, v150
	v_lshl_add_u64 v[160:161], v[160:161], 0, s[92:93]
	s_mov_b32 m0, s31
	ds_read_b128 v[234:237], v0
	ds_read_b128 v[238:241], v0 offset:1024
	ds_read_b128 v[242:245], v0 offset:2048
	ds_read_b128 v[246:249], v0 offset:3072
	global_load_lds_dwordx4 v[160:161], off
	v_lshl_add_u64 v[160:161], v[200:201], 0, s[92:93]
	s_add_i32 m0, s31, 0x2000
	s_nop 0
	global_load_lds_dwordx4 v[160:161], off
	s_barrier
	s_waitcnt lgkmcnt(0)
	s_setprio 1
	s_waitcnt lgkmcnt(0)
	v_mfma_f32_16x16x32_bf16 v[118:121], v[234:237], v[156:159], v[118:121]
	v_mfma_f32_16x16x32_bf16 v[114:117], v[242:245], v[156:159], v[114:117]
	v_mfma_f32_16x16x32_bf16 v[102:105], v[234:237], v[180:183], v[102:105]
	v_mfma_f32_16x16x32_bf16 v[98:101], v[242:245], v[180:183], v[98:101]
	v_mfma_f32_16x16x32_bf16 v[86:89], v[234:237], v[188:191], v[86:89]
	v_mfma_f32_16x16x32_bf16 v[82:85], v[242:245], v[188:191], v[82:85]
	v_mfma_f32_16x16x32_bf16 v[70:73], v[234:237], v[196:199], v[70:73]
	v_mfma_f32_16x16x32_bf16 v[66:69], v[242:245], v[196:199], v[66:69]
	v_mfma_f32_16x16x32_bf16 v[118:121], v[238:241], v[176:179], v[118:121]
	v_mfma_f32_16x16x32_bf16 v[114:117], v[246:249], v[176:179], v[114:117]
	v_mfma_f32_16x16x32_bf16 v[102:105], v[238:241], v[184:187], v[102:105]
	v_mfma_f32_16x16x32_bf16 v[98:101], v[246:249], v[184:187], v[98:101]
	v_mfma_f32_16x16x32_bf16 v[86:89], v[238:241], v[192:195], v[86:89]
	v_mfma_f32_16x16x32_bf16 v[82:85], v[246:249], v[192:195], v[82:85]
	v_mfma_f32_16x16x32_bf16 v[70:73], v[238:241], v[230:233], v[70:73]
	v_mfma_f32_16x16x32_bf16 v[66:69], v[246:249], v[230:233], v[66:69]
	s_setprio 0
	s_mov_b32 m0, s42
	v_lshl_add_u64 v[160:161], v[250:251], 0, s[92:93]
	s_barrier
	ds_read_b128 v[156:159], v151 offset:49152
	ds_read_b128 v[176:179], v151 offset:50176
	ds_read_b128 v[180:183], v151 offset:51200
	ds_read_b128 v[184:187], v151 offset:52224
	ds_read_b128 v[188:191], v151 offset:53248
	ds_read_b128 v[192:195], v151 offset:54272
	ds_read_b128 v[196:199], v151 offset:55296
	ds_read_b128 v[230:233], v151 offset:56320
	global_load_lds_dwordx4 v[160:161], off
	v_lshl_add_u64 v[160:161], v[252:253], 0, s[92:93]
	s_mov_b32 m0, s43
	s_nop 0
	global_load_lds_dwordx4 v[160:161], off
	s_barrier
	s_waitcnt lgkmcnt(0)
	s_setprio 1
	s_waitcnt lgkmcnt(0)
	v_mfma_f32_16x16x32_bf16 v[62:65], v[138:141], v[156:159], v[62:65]
	v_mfma_f32_16x16x32_bf16 v[58:61], v[146:149], v[156:159], v[58:61]
	v_mfma_f32_16x16x32_bf16 v[46:49], v[138:141], v[180:183], v[46:49]
	v_mfma_f32_16x16x32_bf16 v[42:45], v[146:149], v[180:183], v[42:45]
	v_mfma_f32_16x16x32_bf16 v[30:33], v[138:141], v[188:191], v[30:33]
	v_mfma_f32_16x16x32_bf16 v[26:29], v[146:149], v[188:191], v[26:29]
	v_mfma_f32_16x16x32_bf16 v[14:17], v[138:141], v[196:199], v[14:17]
	v_mfma_f32_16x16x32_bf16 v[10:13], v[146:149], v[196:199], v[10:13]
	v_mfma_f32_16x16x32_bf16 v[62:65], v[142:145], v[176:179], v[62:65]
	v_mfma_f32_16x16x32_bf16 v[58:61], v[152:155], v[176:179], v[58:61]
	v_mfma_f32_16x16x32_bf16 v[46:49], v[142:145], v[184:187], v[46:49]
	v_mfma_f32_16x16x32_bf16 v[42:45], v[152:155], v[184:187], v[42:45]
	v_mfma_f32_16x16x32_bf16 v[30:33], v[142:145], v[192:195], v[30:33]
	v_mfma_f32_16x16x32_bf16 v[26:29], v[152:155], v[192:195], v[26:29]
	v_mfma_f32_16x16x32_bf16 v[14:17], v[142:145], v[230:233], v[14:17]
	v_mfma_f32_16x16x32_bf16 v[10:13], v[152:155], v[230:233], v[10:13]
	s_setprio 0
	s_barrier
	s_add_u32 s28, s28, 0x40080
	s_addc_u32 s29, s29, 0
	s_add_i32 s30, s30, s37
	v_lshl_add_u64 v[138:139], s[28:29], 0, v[130:131]
	s_mov_b32 m0, s30
	s_nop 0
	global_load_lds_dwordx4 v[138:139], off
	v_lshl_add_u64 v[138:139], s[28:29], 0, v[132:133]
	s_add_i32 m0, s30, 0x2000
	s_nop 0
	global_load_lds_dwordx4 v[138:139], off
	s_waitcnt vmcnt(6)
	s_barrier
	s_setprio 1
	v_mfma_f32_16x16x32_bf16 v[54:57], v[234:237], v[156:159], v[54:57]
	v_mfma_f32_16x16x32_bf16 v[50:53], v[242:245], v[156:159], v[50:53]
	v_mfma_f32_16x16x32_bf16 v[38:41], v[234:237], v[180:183], v[38:41]
	v_mfma_f32_16x16x32_bf16 v[34:37], v[242:245], v[180:183], v[34:37]
	v_mfma_f32_16x16x32_bf16 v[22:25], v[234:237], v[188:191], v[22:25]
	v_mfma_f32_16x16x32_bf16 v[18:21], v[242:245], v[188:191], v[18:21]
	v_mfma_f32_16x16x32_bf16 v[6:9], v[234:237], v[196:199], v[6:9]
	v_mfma_f32_16x16x32_bf16 v[2:5], v[242:245], v[196:199], v[2:5]
	v_mfma_f32_16x16x32_bf16 v[54:57], v[238:241], v[176:179], v[54:57]
	v_mfma_f32_16x16x32_bf16 v[50:53], v[246:249], v[176:179], v[50:53]
	v_mfma_f32_16x16x32_bf16 v[38:41], v[238:241], v[184:187], v[38:41]
	v_mfma_f32_16x16x32_bf16 v[34:37], v[246:249], v[184:187], v[34:37]
	v_mfma_f32_16x16x32_bf16 v[22:25], v[238:241], v[192:195], v[22:25]
	v_mfma_f32_16x16x32_bf16 v[18:21], v[246:249], v[192:195], v[18:21]
	v_mfma_f32_16x16x32_bf16 v[6:9], v[238:241], v[230:233], v[6:9]
	v_mfma_f32_16x16x32_bf16 v[2:5], v[246:249], v[230:233], v[2:5]
	s_setprio 0
	s_add_i32 s47, s47, 2
	s_add_u32 s34, s34, 0x100
	s_addc_u32 s35, s35, 0
	s_add_u32 s26, s26, 0x100
	s_addc_u32 s27, s27, 0
	s_cmp_gt_u32 s47, 13
	s_barrier
	s_cbranch_scc0 .LBB0_918
	s_cmp_eq_u64 s[4:5], 0
	s_cbranch_scc0 .Lip_nohoist
	s_cmp_eq_u32 s8, 9
	s_cbranch_scc1 .Lip_nohoist
	s_add_u32 s98, s9, 0x40080
	s_addc_u32 s99, s7, 0
	v_lshl_add_u64 v[160:161], s[98:99], 0, v[136:137]
	s_add_i32 m0, s38, 0xc000
	global_load_lds_dwordx4 v[160:161], off
	v_lshl_add_u64 v[160:161], s[98:99], 0, v[134:135]
	s_add_i32 m0, s38, 0xe000
	s_nop 0
	global_load_lds_dwordx4 v[160:161], off
	s_mov_b32 s98, 1
.Lip_nohoist:
	v_mov_b32_e32 v0, v163
	s_movk_i32 s7, 0xffc0
	v_and_b32_e32 v138, 0xc0, v0
	v_and_b32_e32 v139, 15, v0
	v_ashrrev_i32_e32 v140, 2, v0
	v_lshl_or_b32 v152, s8, 8, v138
	v_lshrrev_b32_e32 v0, 1, v0
	v_and_or_b32 v138, v0, 24, v152
	v_and_or_b32 v0, v140, s7, v139
	v_lshl_add_u32 v140, s6, 8, v0
	v_ashrrev_i32_e32 v141, 31, v140
	s_movk_i32 s6, 0x39f
	v_lshlrev_b64 v[144:145], 10, v[140:141]
	v_lshlrev_b64 v[142:143], 4, v[140:141]
	v_lshlrev_b64 v[146:147], 11, v[140:141]
	v_cmp_lt_i32_e64 s[6:7], s6, v138
	s_and_saveexec_b64 s[8:9], s[6:7]
	s_xor_b64 s[8:9], exec, s[8:9]
	s_cbranch_execz .LBB0_931
	s_movk_i32 s19, 0x79f
	v_cmp_lt_u32_e32 vcc, s19, v152
	s_and_saveexec_b64 s[26:27], vcc
	s_xor_b64 s[26:27], exec, s[26:27]
	s_cbranch_execz .LBB0_928
	s_movk_i32 s19, 0x7af
	v_cmp_lt_u32_e32 vcc, s19, v138
	s_and_saveexec_b64 s[28:29], vcc
	s_xor_b64 s[28:29], exec, s[28:29]
	s_cbranch_execz .LBB0_925
	s_movk_i32 s19, 0x9b0
	v_cmp_gt_u32_e32 vcc, s19, v138
	s_and_saveexec_b64 s[30:31], vcc
	s_cbranch_execz .LBB0_924
	v_lshl_add_u64 v[148:149], s[10:11], 0, v[144:145]
	v_mov_b32_e32 v139, v1
	v_lshl_add_u64 v[148:149], v[138:139], 1, v[148:149]
	v_cvt_pk_bf16_f32 v154, v126, v127
	v_cvt_pk_bf16_f32 v155, v128, v129
	v_cvt_pk_bf16_f32 v156, v122, v123
	v_cvt_pk_bf16_f32 v157, v124, v125
	global_store_dwordx4 v[148:149], v[154:157], off offset:-3936
